# XCD-local grid barriers (no L2 writeback / cross-XCD hop) on the 18 seams whose producers and consumers share an XCD, enabled only after a runtime check that every blockIdx%8 group sits on one XCC; pl
# speedup vs baseline: 1.0139x; 1.0036x over previous
_Z8mega_fwd6Params:
	s_mov_b64 s[82:83], s[0:1]
	s_load_dwordx2 s[0:1], s[0:1], 0x100
	s_nop 0
	s_load_dwordx4 s[40:43], s[82:83], 0x210
	s_load_dwordx2 s[26:27], s[82:83], 0x220
	s_add_u32 s4, s82, 0x220
	s_addc_u32 s5, s83, 0
	v_and_b32_e32 v1, 0x3ff, v0
	v_writelane_b32 v252, s4, 0
	v_cmp_gt_u32_e32 vcc, 3, v1
	s_nop 0
	v_writelane_b32 v252, s5, 1
	s_and_saveexec_b64 s[4:5], vcc
	v_lshl_add_u32 v2, v1, 2, 0
	v_add_u32_e32 v2, 0x23800, v2
	v_mov_b32_e32 v3, 0
	ds_write_b32 v2, v3
	s_or_b64 exec, exec, s[4:5]
	s_waitcnt lgkmcnt(0)
	s_barrier
	s_add_u32 s4, s0, 0x300000
	s_getreg_b32 s3, hwreg(HW_REG_XCC_ID, 0, 4)
	s_addc_u32 s5, s1, 0
	s_and_b32 s3, s3, 15
	v_cmp_eq_u32_e32 vcc, 0, v1
	s_and_saveexec_b64 s[6:7], vcc
	s_cbranch_execz .LBB0_5
	s_mov_b64 s[8:9], exec
	v_mbcnt_lo_u32_b32 v2, s8, 0
	v_mbcnt_hi_u32_b32 v2, s9, v2
	v_cmp_eq_u32_e32 vcc, 0, v2
	s_and_b64 s[10:11], exec, vcc
	s_mov_b64 exec, s[10:11]
	s_cbranch_execz .LBB0_5
	s_lshl_b32 s10, s3, 8
	s_bcnt1_i32_b64 s8, s[8:9]
	v_mov_b32_e32 v2, s10
	v_mov_b32_e32 v3, s8
	global_atomic_add v2, v3, s[4:5] offset:1024
	s_and_b32 s10, s2, 7
	s_lshl_b32 s10, s10, 2
	s_addk_i32 s10, 0x3800
	s_lshl_b32 s8, 1, s3
	v_mov_b32_e32 v2, s10
	v_mov_b32_e32 v3, s8
	global_atomic_or v2, v3, s[4:5]

.LBB0_95:
	s_andn2_saveexec_b64 s[6:7], s[6:7]
	s_cbranch_execz .LBB0_115
	s_mov_b64 s[6:7], exec
	s_mov_b32 s1, 0xcd99adac
	s_lshr_b32 s1, s1, s21
	s_bitcmp1_b32 s1, 0
	s_cbranch_scc0 .Lbar_full
	v_mov_b32_e32 v20, 0x23808
	ds_read_b32 v21, v20
	s_waitcnt lgkmcnt(0)
	v_readfirstlane_b32 s1, v21
	s_cmp_lg_u32 s1, 0
	s_cbranch_scc1 .Lbar_have_flag
	v_mov_b32_e32 v22, 0x3600
	global_load_dwordx4 v[24:27], v22, s[24:25] sc1
	global_load_dwordx4 v[28:31], v22, s[24:25] offset:16 sc1
	s_waitcnt vmcnt(0)
	v_add_u32_e32 v21, -1, v24
	v_and_b32_e32 v23, v21, v24
	v_min_u32_e32 v22, v24, v25
	v_add_u32_e32 v21, -1, v25
	v_and_b32_e32 v21, v21, v25
	v_or_b32_e32 v23, v23, v21
	v_add_u32_e32 v21, -1, v26
	v_and_b32_e32 v21, v21, v26
	v_or_b32_e32 v23, v23, v21
	v_min_u32_e32 v22, v22, v26
	v_add_u32_e32 v21, -1, v27
	v_and_b32_e32 v21, v21, v27
	v_or_b32_e32 v23, v23, v21
	v_min_u32_e32 v22, v22, v27
	v_add_u32_e32 v21, -1, v28
	v_and_b32_e32 v21, v21, v28
	v_or_b32_e32 v23, v23, v21
	v_min_u32_e32 v22, v22, v28
	v_add_u32_e32 v21, -1, v29
	v_and_b32_e32 v21, v21, v29
	v_or_b32_e32 v23, v23, v21
	v_min_u32_e32 v22, v22, v29
	v_add_u32_e32 v21, -1, v30
	v_and_b32_e32 v21, v21, v30
	v_or_b32_e32 v23, v23, v21
	v_min_u32_e32 v22, v22, v30
	v_add_u32_e32 v21, -1, v31
	v_and_b32_e32 v21, v21, v31
	v_or_b32_e32 v23, v23, v21
	v_min_u32_e32 v22, v22, v31
	v_cmp_eq_u32_e32 vcc, 0, v23
	v_cmp_ne_u32_e64 s[10:11], 0, v22
	s_and_b64 s[10:11], s[10:11], vcc
	v_cndmask_b32_e64 v21, 2, 1, s[10:11]
	ds_write_b32 v20, v21
	s_nop 1
	v_readfirstlane_b32 s1, v21
.Lbar_have_flag:
	s_cmp_eq_u32 s1, 1
	s_cbranch_scc0 .Lbar_full
	s_branch .LBB0_112
.Lbar_full:
	buffer_wbl2 sc1
	s_waitcnt lgkmcnt(0)
	s_waitcnt vmcnt(0)
	v_mbcnt_lo_u32_b32 v1, s6, 0
	v_mbcnt_hi_u32_b32 v1, s7, v1
	v_cmp_eq_u32_e32 vcc, 0, v1
	s_and_saveexec_b64 s[8:9], vcc
	s_cbranch_execz .LBB0_98
	s_bcnt1_i32_b64 s1, s[6:7]
	v_readlane_b32 s6, v252, 57
	v_mov_b32_e32 v2, s1
	v_readlane_b32 s7, v252, 58
	s_nop 4
	global_atomic_add v2, v169, v2, s[6:7] sc0
